# cross-attention: next q tile prefetched into spare registers during the current tile (next-block prefetch in loop slack)
# speedup vs baseline: 1.0149x; 1.0149x over previous
; __device__ __forceinline__ void cross_unit(lbyte* lds, bf16* CQ, const bf16* CKV, const float* gq, const float* gk, int layer, int b, int hc, int qblk0, int qstep, int nq) {
;     ...
;     __syncthreads();
; #pragma unroll 1
;     for (int qi = 0; qi < nq; ++qi) { const int qblk = qblk0 + qi * qstep;
;     const size_t row = (size_t)b * SEQ + qblk * 256 + 32 * wid + l31;
;     bf16* qrow = CQ + row * 512 + hc * 128;
;     s16x8 qf[8];
; #pragma unroll
;     for (int c = 0; c < 8; ++c) qf[c] = *(const s16x8*)(qrow + 16 * c + 8 * h);
.LBB0_985:
	s_or_b64 exec, exec, s[0:1]
	v_readlane_b32 s0, v255, 8
	v_readlane_b32 s1, v255, 9
	s_andn2_b64 vcc, exec, s[0:1]
	s_waitcnt vmcnt(0) lgkmcnt(0)
	s_barrier
	s_cbranch_vccnz .LBB0_993
	s_add_u32 s6, s5, 0x1ac00000
	s_addc_u32 s7, s4, 0
	s_lshl_b64 s[0:1], s[86:87], 2
	s_add_u32 s0, s9, s0
	s_addc_u32 s1, s8, s1
	s_ashr_i32 s4, s10, 1
	v_readlane_b32 s8, v254, 14
	v_and_b32_e32 v4, 31, v5
	s_andn2_b32 s4, s4, 31
	v_readlane_b32 s9, v254, 15
	s_ashr_i32 s5, s4, 31
	v_or_b32_e32 v2, s8, v4
	v_mov_b32_e32 v3, s9
	v_lshl_add_u64 v[148:149], v[2:3], 0, s[4:5]
	v_readlane_b32 s4, v254, 16
	v_readlane_b32 s5, v254, 17
	v_bfe_u32 v5, v5, 5, 1
	s_lshl_b64 s[4:5], s[4:5], 1
	s_add_u32 s4, s6, s4
	v_lshlrev_b32_e32 v0, 5, v5
	s_addc_u32 s5, s7, s5
	v_lshl_add_u64 v[150:151], s[0:1], 0, v[0:1]
	v_lshlrev_b32_e32 v0, 4, v5
	v_mul_u32_u24_e32 v2, 0x210, v4
	v_lshl_add_u64 v[152:153], s[4:5], 0, v[0:1]
	v_lshl_or_b32 v156, v5, 3, v2
	v_mad_u32_u24 v157, v4, s29, v0
	s_mov_b32 s0, 0
	s_mov_b32 s7, 0
	v_readlane_b32 s6, v254, 63
	s_nop 0
	s_mul_i32 s6, s7, s6
	s_add_i32 s6, s6, s68
	s_lshl_b32 s8, s6, 8
	s_ashr_i32 s9, s8, 31
	v_lshl_add_u64 v[228:229], v[148:149], 0, s[8:9]
	v_lshlrev_b64 v[228:229], 10, v[228:229]
	v_lshl_add_u64 v[228:229], v[152:153], 0, v[228:229]
	global_load_dwordx4 v[196:199], v[228:229], off offset:224
	global_load_dwordx4 v[200:203], v[228:229], off offset:192
	global_load_dwordx4 v[204:207], v[228:229], off offset:160
	global_load_dwordx4 v[208:211], v[228:229], off offset:128
	global_load_dwordx4 v[212:215], v[228:229], off offset:96
	global_load_dwordx4 v[216:219], v[228:229], off offset:64
	global_load_dwordx4 v[220:223], v[228:229], off offset:32
	global_load_dwordx4 v[224:227], v[228:229], off
	s_branch .LBB0_988

; __device__ __forceinline__ unsigned pk2(float lo, float hi) { f32x2_t v = {lo, hi}; bf16x2_t b = __builtin_convertvector(v, bf16x2_t); return __builtin_bit_cast(unsigned, b); }
; __device__ __forceinline__ float pair_sum(float v) { auto r = __builtin_amdgcn_permlane32_swap(__float_as_uint(v), __float_as_uint(v), false, false); return __uint_as_float(r[0]) + __uint_as_float(r[1]); }
; __device__ __forceinline__ void cross_unit(lbyte* lds, bf16* CQ, const bf16* CKV, const float* gq, const float* gk, int layer, int b, int hc, int qblk0, int qstep, int nq) {
;     ...
;     for (int qi = 0; qi < nq; ++qi) { const int qblk = qblk0 + qi * qstep;
;     const size_t row = (size_t)b * SEQ + qblk * 256 + 32 * wid + l31;
;     bf16* qrow = CQ + row * 512 + hc * 128;
;     s16x8 qf[8];
; #pragma unroll
;     for (int c = 0; c < 8; ++c) qf[c] = *(const s16x8*)(qrow + 16 * c + 8 * h);
;     { float ss = 0.f;
; #pragma unroll
;       for (int c = 0; c < 8; ++c)
; #pragma unroll
;           for (int e2 = 0; e2 < 8; ++e2) { const float f = bf2f((unsigned short)qf[c][e2]); ss += f * f; }
;       ss = pair_sum(ss); const float rn = __builtin_amdgcn_rsqf(ss * (1.0f / 128.0f) + 1e-6f);
; #pragma unroll
;       for (int c = 0; c < 8; ++c) { const f32x4 ga = *(const f32x4*)(gq + 16 * c + 8 * h), gb = *(const f32x4*)(gq + 16 * c + 8 * h + 4); u32x4 w;
;           w.x = pk2(bf2f((unsigned short)qf[c][0]) * rn * ga[0], bf2f((unsigned short)qf[c][1]) * rn * ga[1]); w.y = pk2(bf2f((unsigned short)qf[c][2]) * rn * ga[2], bf2f((unsigned short)qf[c][3]) * rn * ga[3]);
;           w.z = pk2(bf2f((unsigned short)qf[c][4]) * rn * gb[0], bf2f((unsigned short)qf[c][5]) * rn * gb[1]); w.w = pk2(bf2f((unsigned short)qf[c][6]) * rn * gb[2], bf2f((unsigned short)qf[c][7]) * rn * gb[3]);
;           qf[c] = __builtin_bit_cast(s16x8, w); } }
.LBB0_988:
	v_readlane_b32 s1, v254, 63
	s_mul_i32 s1, s0, s1
	s_add_i32 s1, s1, s68
	s_lshl_b32 s4, s1, 8
	s_ashr_i32 s5, s4, 31
	v_lshl_add_u64 v[2:3], v[148:149], 0, s[4:5]
	v_lshlrev_b64 v[2:3], 10, v[2:3]
	v_lshl_add_u64 v[154:155], v[152:153], 0, v[2:3]
	global_load_dwordx4 v[50:53], v[150:151], off offset:16
	global_load_dwordx4 v[54:57], v[150:151], off
	global_load_dwordx4 v[42:45], v[150:151], off offset:80
	global_load_dwordx4 v[46:49], v[150:151], off offset:64
	global_load_dwordx4 v[34:37], v[150:151], off offset:144
	global_load_dwordx4 v[38:41], v[150:151], off offset:128
	global_load_dwordx4 v[26:29], v[150:151], off offset:208
	global_load_dwordx4 v[30:33], v[150:151], off offset:192
	global_load_dwordx4 v[18:21], v[150:151], off offset:272
	global_load_dwordx4 v[22:25], v[150:151], off offset:256
	global_load_dwordx4 v[10:13], v[150:151], off offset:336
	global_load_dwordx4 v[14:17], v[150:151], off offset:320
	global_load_dwordx4 v[2:5], v[150:151], off offset:400
	global_load_dwordx4 v[6:9], v[150:151], off offset:384
	global_load_dwordx4 v[126:129], v[150:151], off offset:464
	global_load_dwordx4 v[130:133], v[150:151], off offset:448
	s_mov_b32 s1, 8
	v_mov_b32_e32 v158, 0
	v_mov_b32_e32 v162, 0xf149f2ca
	v_mov_b32_e32 v159, v157
	v_mov_b32_e32 v160, v156
	s_waitcnt vmcnt(23)
	v_and_b32_e32 v59, 0xffff0000, v199
	v_lshlrev_b32_e32 v58, 16, v199
	v_and_b32_e32 v61, 0xffff0000, v198
	v_lshlrev_b32_e32 v60, 16, v198
	s_waitcnt vmcnt(19)
	v_and_b32_e32 v95, 0xffff0000, v213
	v_lshlrev_b32_e32 v94, 16, v213
	v_and_b32_e32 v113, 0xffff0000, v212
	s_waitcnt vmcnt(16)
	v_and_b32_e32 v97, 0xffff0000, v224
	v_lshlrev_b32_e32 v112, 16, v212
	v_lshlrev_b32_e32 v96, 16, v224
	v_and_b32_e32 v67, 0xffff0000, v203
	v_lshlrev_b32_e32 v66, 16, v203
	v_and_b32_e32 v69, 0xffff0000, v202
	v_lshlrev_b32_e32 v68, 16, v202
	v_and_b32_e32 v75, 0xffff0000, v207
	v_lshlrev_b32_e32 v74, 16, v207
	v_and_b32_e32 v77, 0xffff0000, v206
	v_lshlrev_b32_e32 v76, 16, v206
	v_and_b32_e32 v83, 0xffff0000, v211
	v_lshlrev_b32_e32 v82, 16, v211
	v_and_b32_e32 v85, 0xffff0000, v210
	v_lshlrev_b32_e32 v84, 16, v210
	v_and_b32_e32 v91, 0xffff0000, v215
	v_lshlrev_b32_e32 v90, 16, v215
	v_and_b32_e32 v93, 0xffff0000, v214
	v_lshlrev_b32_e32 v92, 16, v214
	v_and_b32_e32 v115, 0xffff0000, v219
	v_lshlrev_b32_e32 v114, 16, v219
	v_and_b32_e32 v117, 0xffff0000, v218
	v_lshlrev_b32_e32 v116, 16, v218
	v_and_b32_e32 v119, 0xffff0000, v217
	v_lshlrev_b32_e32 v118, 16, v217
	v_and_b32_e32 v121, 0xffff0000, v216
	v_lshlrev_b32_e32 v120, 16, v216
	v_and_b32_e32 v123, 0xffff0000, v223
	v_lshlrev_b32_e32 v122, 16, v223
	v_and_b32_e32 v103, 0xffff0000, v222
	v_lshlrev_b32_e32 v102, 16, v222
	v_and_b32_e32 v107, 0xffff0000, v221
	v_lshlrev_b32_e32 v106, 16, v221
	v_and_b32_e32 v101, 0xffff0000, v220
	v_lshlrev_b32_e32 v100, 16, v220
	v_and_b32_e32 v105, 0xffff0000, v227
	v_lshlrev_b32_e32 v104, 16, v227
	v_and_b32_e32 v99, 0xffff0000, v226
	v_lshlrev_b32_e32 v98, 16, v226
	v_and_b32_e32 v111, 0xffff0000, v225
	v_lshlrev_b32_e32 v110, 16, v225
	v_pk_mul_f32 v[108:109], v[96:97], v[96:97]
	v_pk_fma_f32 v[108:109], v[110:111], v[110:111], v[108:109]
	v_and_b32_e32 v87, 0xffff0000, v209
	v_pk_fma_f32 v[108:109], v[98:99], v[98:99], v[108:109]
	v_pk_fma_f32 v[108:109], v[104:105], v[104:105], v[108:109]
	v_pk_fma_f32 v[108:109], v[100:101], v[100:101], v[108:109]
	v_pk_fma_f32 v[108:109], v[106:107], v[106:107], v[108:109]
	v_pk_fma_f32 v[108:109], v[102:103], v[102:103], v[108:109]
	v_pk_fma_f32 v[108:109], v[122:123], v[122:123], v[108:109]
	v_pk_fma_f32 v[108:109], v[120:121], v[120:121], v[108:109]
	v_pk_fma_f32 v[108:109], v[118:119], v[118:119], v[108:109]
	v_pk_fma_f32 v[108:109], v[116:117], v[116:117], v[108:109]
	v_pk_fma_f32 v[108:109], v[114:115], v[114:115], v[108:109]
	v_pk_fma_f32 v[108:109], v[112:113], v[112:113], v[108:109]
	v_pk_fma_f32 v[108:109], v[94:95], v[94:95], v[108:109]
	v_pk_fma_f32 v[108:109], v[92:93], v[92:93], v[108:109]
	v_pk_fma_f32 v[108:109], v[90:91], v[90:91], v[108:109]
	v_lshlrev_b32_e32 v86, 16, v209
	v_and_b32_e32 v89, 0xffff0000, v208
	v_lshlrev_b32_e32 v88, 16, v208
	v_pk_fma_f32 v[108:109], v[88:89], v[88:89], v[108:109]
	v_pk_fma_f32 v[108:109], v[86:87], v[86:87], v[108:109]
	v_pk_fma_f32 v[108:109], v[84:85], v[84:85], v[108:109]
	v_pk_fma_f32 v[108:109], v[82:83], v[82:83], v[108:109]
	v_and_b32_e32 v79, 0xffff0000, v205
	v_lshlrev_b32_e32 v78, 16, v205
	v_and_b32_e32 v81, 0xffff0000, v204
	v_lshlrev_b32_e32 v80, 16, v204
	v_pk_fma_f32 v[108:109], v[80:81], v[80:81], v[108:109]
	v_pk_fma_f32 v[108:109], v[78:79], v[78:79], v[108:109]
	v_pk_fma_f32 v[108:109], v[76:77], v[76:77], v[108:109]
	v_pk_fma_f32 v[108:109], v[74:75], v[74:75], v[108:109]
	v_and_b32_e32 v71, 0xffff0000, v201
	v_lshlrev_b32_e32 v70, 16, v201
	v_and_b32_e32 v73, 0xffff0000, v200
	v_lshlrev_b32_e32 v72, 16, v200
	v_pk_fma_f32 v[108:109], v[72:73], v[72:73], v[108:109]
	v_pk_fma_f32 v[108:109], v[70:71], v[70:71], v[108:109]
	v_pk_fma_f32 v[108:109], v[68:69], v[68:69], v[108:109]
	v_pk_fma_f32 v[108:109], v[66:67], v[66:67], v[108:109]
	v_and_b32_e32 v63, 0xffff0000, v197
	v_lshlrev_b32_e32 v62, 16, v197
	v_and_b32_e32 v65, 0xffff0000, v196
	v_lshlrev_b32_e32 v64, 16, v196
	v_pk_fma_f32 v[108:109], v[64:65], v[64:65], v[108:109]
	v_pk_fma_f32 v[108:109], v[62:63], v[62:63], v[108:109]
	v_pk_fma_f32 v[108:109], v[60:61], v[60:61], v[108:109]
	v_pk_fma_f32 v[108:109], v[58:59], v[58:59], v[108:109]
	v_add_f32_e32 v108, v108, v109
	v_mov_b32_e32 v0, v108
	s_nop 1
	v_permlane32_swap_b32_e32 v108, v0
	v_add_f32_e32 v0, v108, v0
	v_fmamk_f32 v0, v0, 0x3c000000, v233
	v_rsq_f32_e32 v0, v0
	s_nop 0
	v_pk_mul_f32 v[96:97], v[0:1], v[96:97] op_sel_hi:[0,1]
	s_waitcnt vmcnt(14)
; __device__ __forceinline__ unsigned pk2(float lo, float hi) { f32x2_t v = {lo, hi}; bf16x2_t b = __builtin_convertvector(v, bf16x2_t); return __builtin_bit_cast(unsigned, b); }
; __device__ __forceinline__ float pair_sum(float v) { auto r = __builtin_amdgcn_permlane32_swap(__float_as_uint(v), __float_as_uint(v), false, false); return __uint_as_float(r[0]) + __uint_as_float(r[1]); }
; __device__ __forceinline__ void cross_unit(lbyte* lds, bf16* CQ, const bf16* CKV, const float* gq, const float* gk, int layer, int b, int hc, int qblk0, int qstep, int nq) {
;     ...
;     for (int qi = 0; qi < nq; ++qi) { const int qblk = qblk0 + qi * qstep;
;     const size_t row = (size_t)b * SEQ + qblk * 256 + 32 * wid + l31;
;     bf16* qrow = CQ + row * 512 + hc * 128;
;     s16x8 qf[8];
; #pragma unroll
;     for (int c = 0; c < 8; ++c) qf[c] = *(const s16x8*)(qrow + 16 * c + 8 * h);
;     ...
;       ss = pair_sum(ss); const float rn = __builtin_amdgcn_rsqf(ss * (1.0f / 128.0f) + 1e-6f);
; #pragma unroll
;       for (int c = 0; c < 8; ++c) { const f32x4 ga = *(const f32x4*)(gq + 16 * c + 8 * h), gb = *(const f32x4*)(gq + 16 * c + 8 * h + 4); u32x4 w;
;           w.x = pk2(bf2f((unsigned short)qf[c][0]) * rn * ga[0], bf2f((unsigned short)qf[c][1]) * rn * ga[1]); w.y = pk2(bf2f((unsigned short)qf[c][2]) * rn * ga[2], bf2f((unsigned short)qf[c][3]) * rn * ga[3]);
;           w.z = pk2(bf2f((unsigned short)qf[c][4]) * rn * gb[0], bf2f((unsigned short)qf[c][5]) * rn * gb[1]); w.w = pk2(bf2f((unsigned short)qf[c][6]) * rn * gb[2], bf2f((unsigned short)qf[c][7]) * rn * gb[3]);
;           qf[c] = __builtin_bit_cast(s16x8, w); } }
;     f32x16 o[4];
; #pragma unroll
;     for (int r = 0; r < 16; ++r) { o[0][r] = 0.f; o[1][r] = 0.f; o[2][r] = 0.f; o[3][r] = 0.f; }
	v_pk_mul_f32 v[54:55], v[54:55], v[96:97]
	s_nop 0
	v_cvt_pk_bf16_f32 v96, v54, v55
	v_pk_mul_f32 v[54:55], v[0:1], v[110:111] op_sel_hi:[0,1]
	v_pk_mul_f32 v[54:55], v[56:57], v[54:55]
	s_nop 0
	v_cvt_pk_bf16_f32 v97, v54, v55
	v_pk_mul_f32 v[54:55], v[0:1], v[98:99] op_sel_hi:[0,1]
	v_pk_mul_f32 v[50:51], v[50:51], v[54:55]
	s_nop 0
	v_cvt_pk_bf16_f32 v98, v50, v51
	v_pk_mul_f32 v[50:51], v[0:1], v[104:105] op_sel_hi:[0,1]
	v_pk_mul_f32 v[50:51], v[52:53], v[50:51]
	s_nop 0
	v_cvt_pk_bf16_f32 v99, v50, v51
	v_pk_mul_f32 v[50:51], v[0:1], v[100:101] op_sel_hi:[0,1]
	s_waitcnt vmcnt(12)
	v_pk_mul_f32 v[46:47], v[46:47], v[50:51]
	s_nop 0
	v_cvt_pk_bf16_f32 v100, v46, v47
	v_pk_mul_f32 v[46:47], v[0:1], v[106:107] op_sel_hi:[0,1]
	v_pk_mul_f32 v[46:47], v[48:49], v[46:47]
	s_nop 0
	v_cvt_pk_bf16_f32 v101, v46, v47
	v_pk_mul_f32 v[46:47], v[0:1], v[102:103] op_sel_hi:[0,1]
	v_pk_mul_f32 v[42:43], v[42:43], v[46:47]
	s_nop 0
	v_cvt_pk_bf16_f32 v102, v42, v43
	v_pk_mul_f32 v[42:43], v[0:1], v[122:123] op_sel_hi:[0,1]
	v_pk_mul_f32 v[42:43], v[44:45], v[42:43]
	s_nop 0
	v_cvt_pk_bf16_f32 v103, v42, v43
	v_pk_mul_f32 v[42:43], v[0:1], v[120:121] op_sel_hi:[0,1]
	s_waitcnt vmcnt(10)
	v_pk_mul_f32 v[38:39], v[38:39], v[42:43]
	s_nop 0
	v_cvt_pk_bf16_f32 v104, v38, v39
	v_pk_mul_f32 v[38:39], v[0:1], v[118:119] op_sel_hi:[0,1]
	v_pk_mul_f32 v[38:39], v[40:41], v[38:39]
	s_nop 0
	v_cvt_pk_bf16_f32 v105, v38, v39
	v_pk_mul_f32 v[38:39], v[0:1], v[116:117] op_sel_hi:[0,1]
	v_pk_mul_f32 v[34:35], v[34:35], v[38:39]
	s_nop 0
	v_cvt_pk_bf16_f32 v106, v34, v35
	v_pk_mul_f32 v[34:35], v[0:1], v[114:115] op_sel_hi:[0,1]
	v_pk_mul_f32 v[34:35], v[36:37], v[34:35]
	s_nop 0
	v_cvt_pk_bf16_f32 v107, v34, v35
	v_pk_mul_f32 v[34:35], v[0:1], v[112:113] op_sel_hi:[0,1]
	s_waitcnt vmcnt(8)
	v_pk_mul_f32 v[30:31], v[34:35], v[30:31]
	s_nop 0
	v_cvt_pk_bf16_f32 v108, v30, v31
	v_pk_mul_f32 v[30:31], v[0:1], v[94:95] op_sel_hi:[0,1]
	v_pk_mul_f32 v[30:31], v[30:31], v[32:33]
	s_nop 0
	v_cvt_pk_bf16_f32 v109, v30, v31
	v_pk_mul_f32 v[30:31], v[0:1], v[92:93] op_sel_hi:[0,1]
	v_pk_mul_f32 v[26:27], v[30:31], v[26:27]
	s_nop 0
	v_cvt_pk_bf16_f32 v110, v26, v27
	v_pk_mul_f32 v[26:27], v[0:1], v[90:91] op_sel_hi:[0,1]
	v_pk_mul_f32 v[26:27], v[26:27], v[28:29]
	s_nop 0
	v_cvt_pk_bf16_f32 v111, v26, v27
	v_pk_mul_f32 v[26:27], v[0:1], v[88:89] op_sel_hi:[0,1]
	s_waitcnt vmcnt(6)
	v_pk_mul_f32 v[22:23], v[26:27], v[22:23]
	s_nop 0
	v_cvt_pk_bf16_f32 v112, v22, v23
	v_pk_mul_f32 v[22:23], v[0:1], v[86:87] op_sel_hi:[0,1]
	v_pk_mul_f32 v[22:23], v[22:23], v[24:25]
	s_nop 0
	v_cvt_pk_bf16_f32 v113, v22, v23
	v_pk_mul_f32 v[22:23], v[0:1], v[84:85] op_sel_hi:[0,1]
	v_pk_mul_f32 v[18:19], v[22:23], v[18:19]
	s_nop 0
	v_cvt_pk_bf16_f32 v114, v18, v19
	v_pk_mul_f32 v[18:19], v[0:1], v[82:83] op_sel_hi:[0,1]
	v_pk_mul_f32 v[18:19], v[18:19], v[20:21]
	s_nop 0
	v_cvt_pk_bf16_f32 v115, v18, v19
	v_pk_mul_f32 v[18:19], v[0:1], v[80:81] op_sel_hi:[0,1]
	s_waitcnt vmcnt(4)
	v_pk_mul_f32 v[14:15], v[18:19], v[14:15]
	s_nop 0
	v_cvt_pk_bf16_f32 v116, v14, v15
	v_pk_mul_f32 v[14:15], v[0:1], v[78:79] op_sel_hi:[0,1]
	v_pk_mul_f32 v[14:15], v[14:15], v[16:17]
	s_nop 0
	v_cvt_pk_bf16_f32 v117, v14, v15
	v_pk_mul_f32 v[14:15], v[0:1], v[76:77] op_sel_hi:[0,1]
	v_pk_mul_f32 v[10:11], v[14:15], v[10:11]
	v_mov_b32_e32 v14, v1
	v_cvt_pk_bf16_f32 v118, v10, v11
	v_pk_mul_f32 v[10:11], v[0:1], v[74:75] op_sel_hi:[0,1]
	v_pk_mul_f32 v[10:11], v[10:11], v[12:13]
	v_mov_b32_e32 v15, v1
	v_cvt_pk_bf16_f32 v119, v10, v11
	v_pk_mul_f32 v[10:11], v[0:1], v[72:73] op_sel_hi:[0,1]
	s_waitcnt vmcnt(2)
	v_pk_mul_f32 v[6:7], v[10:11], v[6:7]
	v_mov_b32_e32 v10, v1
	v_cvt_pk_bf16_f32 v120, v6, v7
	v_pk_mul_f32 v[6:7], v[0:1], v[70:71] op_sel_hi:[0,1]
	v_pk_mul_f32 v[6:7], v[6:7], v[8:9]
	v_mov_b32_e32 v8, v1
	v_cvt_pk_bf16_f32 v121, v6, v7
	v_pk_mul_f32 v[6:7], v[0:1], v[68:69] op_sel_hi:[0,1]
	v_pk_mul_f32 v[2:3], v[6:7], v[2:3]
	v_mov_b32_e32 v6, v1
	v_cvt_pk_bf16_f32 v122, v2, v3
	v_pk_mul_f32 v[2:3], v[0:1], v[66:67] op_sel_hi:[0,1]
	v_pk_mul_f32 v[2:3], v[2:3], v[4:5]
	v_mov_b32_e32 v4, v1
	v_cvt_pk_bf16_f32 v123, v2, v3
	v_pk_mul_f32 v[2:3], v[0:1], v[64:65] op_sel_hi:[0,1]
	s_waitcnt vmcnt(0)
	s_add_i32 s7, s0, 1
	v_readlane_b32 s6, v255, 7
	s_nop 0
	s_cmp_lt_u32 s7, s6
	s_cbranch_scc0 .Lcxq_nopf
	v_readlane_b32 s6, v254, 63
	s_nop 0
	s_mul_i32 s6, s7, s6
	s_add_i32 s6, s6, s68
	s_lshl_b32 s8, s6, 8
	s_ashr_i32 s9, s8, 31
	v_lshl_add_u64 v[228:229], v[148:149], 0, s[8:9]
	v_lshlrev_b64 v[228:229], 10, v[228:229]
	v_lshl_add_u64 v[228:229], v[152:153], 0, v[228:229]
	global_load_dwordx4 v[196:199], v[228:229], off offset:224
	global_load_dwordx4 v[200:203], v[228:229], off offset:192
	global_load_dwordx4 v[204:207], v[228:229], off offset:160
	global_load_dwordx4 v[208:211], v[228:229], off offset:128
	global_load_dwordx4 v[212:215], v[228:229], off offset:96
	global_load_dwordx4 v[216:219], v[228:229], off offset:64
	global_load_dwordx4 v[220:223], v[228:229], off offset:32
	global_load_dwordx4 v[224:227], v[228:229], off
.Lcxq_nopf:
	v_pk_mul_f32 v[2:3], v[2:3], v[130:131]
	v_mov_b32_e32 v5, v1
	v_cvt_pk_bf16_f32 v124, v2, v3
	v_pk_mul_f32 v[2:3], v[0:1], v[62:63] op_sel_hi:[0,1]
	v_pk_mul_f32 v[2:3], v[2:3], v[132:133]
	v_mov_b32_e32 v7, v1
	v_cvt_pk_bf16_f32 v125, v2, v3
	v_pk_mul_f32 v[2:3], v[0:1], v[60:61] op_sel_hi:[0,1]
	v_pk_mul_f32 v[2:3], v[2:3], v[126:127]
	v_mov_b32_e32 v9, v1
	v_cvt_pk_bf16_f32 v126, v2, v3
	v_pk_mul_f32 v[2:3], v[0:1], v[58:59] op_sel_hi:[0,1]
	v_pk_mul_f32 v[2:3], v[2:3], v[128:129]
	v_mov_b32_e32 v0, v1
	v_cvt_pk_bf16_f32 v127, v2, v3
	v_mov_b32_e32 v2, v1
	v_mov_b32_e32 v3, v1
	v_mov_b32_e32 v11, v1
	v_mov_b32_e32 v12, v1
	v_mov_b32_e32 v13, v1
	v_mov_b64_e32 v[30:31], v[14:15]
	v_mov_b64_e32 v[46:47], v[14:15]
	v_mov_b64_e32 v[62:63], v[14:15]
	v_mov_b64_e32 v[78:79], v[14:15]
	v_mov_b64_e32 v[28:29], v[12:13]
	v_mov_b64_e32 v[26:27], v[10:11]
	v_mov_b64_e32 v[24:25], v[8:9]
	v_mov_b64_e32 v[22:23], v[6:7]
	v_mov_b64_e32 v[20:21], v[4:5]
	v_mov_b64_e32 v[18:19], v[2:3]
	v_mov_b64_e32 v[16:17], v[0:1]
	v_mov_b64_e32 v[44:45], v[12:13]
	v_mov_b64_e32 v[42:43], v[10:11]
	v_mov_b64_e32 v[40:41], v[8:9]
	v_mov_b64_e32 v[38:39], v[6:7]
	v_mov_b64_e32 v[36:37], v[4:5]
	v_mov_b64_e32 v[34:35], v[2:3]
	v_mov_b64_e32 v[32:33], v[0:1]
	v_mov_b64_e32 v[60:61], v[12:13]
	v_mov_b64_e32 v[58:59], v[10:11]
	v_mov_b64_e32 v[56:57], v[8:9]
	v_mov_b64_e32 v[54:55], v[6:7]
	v_mov_b64_e32 v[52:53], v[4:5]
	v_mov_b64_e32 v[50:51], v[2:3]
	v_mov_b64_e32 v[48:49], v[0:1]
	v_mov_b64_e32 v[76:77], v[12:13]
	v_mov_b64_e32 v[74:75], v[10:11]
	v_mov_b64_e32 v[72:73], v[8:9]
	v_mov_b64_e32 v[70:71], v[6:7]
	v_mov_b64_e32 v[68:69], v[4:5]
	v_mov_b64_e32 v[66:67], v[2:3]
	v_mov_b64_e32 v[64:65], v[0:1]
